# nt hint also on the gated-norm pass loads and the fix-up pass loads
# speedup vs baseline: 1.3918x; 1.0048x over previous
.LBB0_678:
	s_or_b64 exec, exec, s[6:7]
	s_lshl_b32 s0, s2, 3
	s_add_i32 s3, s44, s0
	s_cmp_gt_i32 s3, 0xffff
	s_waitcnt lgkmcnt(0)
	s_barrier
	s_cbranch_scc1 .LBB0_689
	v_readlane_b32 s16, v233, 23
	v_readlane_b32 s17, v233, 24
	s_and_b32 s0, s3, 3
	s_lshr_b32 s1, s3, 2
	s_lshl_b32 s1, s1, 5
	s_lshl_b32 s4, s0, 9
	s_lshl_b32 s6, s1, 11
	s_add_u32 s6, s6, s4
	s_add_u32 s6, s6, 0xcc00000
	s_add_u32 s10, s48, s6
	s_addc_u32 s11, s49, 0
	s_lshl_b32 s4, s0, 8
	s_mul_i32 s6, s1, 0x1c00
	s_add_u32 s6, s6, s4
	s_add_u32 s6, s6, 0x3c00c00
	s_add_u32 s12, s48, s6
	s_addc_u32 s13, s49, 0
	s_lshl_b32 s6, s1, 11
	s_add_u32 s6, s6, s4
	s_add_u32 s6, s6, 0xac00000
	s_add_u32 s14, s48, s6
	s_addc_u32 s15, s49, 0
	v_lshrrev_b32_e32 v84, 3, v218
	v_and_b32_e32 v85, 7, v218
	v_lshlrev_b32_e32 v86, 11, v84
	v_lshl_or_b32 v86, v85, 4, v86
	v_mul_u32_u24_e32 v87, 0x1c00, v84
	v_lshl_or_b32 v87, v85, 3, v87
	v_lshlrev_b32_e32 v88, 11, v84
	v_lshl_or_b32 v88, v85, 3, v88
	v_lshlrev_b32_e32 v89, 4, v85
	global_load_dwordx4 v[64:67], v89, s[16:17]
	global_load_dwordx4 v[68:71], v89, s[16:17] offset:128
	global_load_dwordx4 v[72:75], v89, s[16:17] offset:256
	global_load_dwordx4 v[76:79], v89, s[16:17] offset:384
	v_mov_b32_e32 v82, 0x358637bd
	global_load_dwordx4 v[0:3], v86, s[10:11] nt
	global_load_dwordx4 v[4:7], v86, s[10:11] offset:128 nt
	global_load_dwordx4 v[8:11], v86, s[10:11] offset:256 nt
	global_load_dwordx4 v[12:15], v86, s[10:11] offset:384 nt
	global_load_dwordx2 v[16:17], v87, s[12:13] nt
	global_load_dwordx2 v[18:19], v87, s[12:13] offset:64 nt
	global_load_dwordx2 v[20:21], v87, s[12:13] offset:128 nt
	global_load_dwordx2 v[22:23], v87, s[12:13] offset:192 nt
	s_add_u32 s10, s10, 0x4000
	s_addc_u32 s11, s11, 0
	s_add_u32 s12, s12, 0xe000
	s_addc_u32 s13, s13, 0
	global_load_dwordx4 v[32:35], v86, s[10:11] nt
	global_load_dwordx4 v[36:39], v86, s[10:11] offset:128 nt
	global_load_dwordx4 v[40:43], v86, s[10:11] offset:256 nt
	global_load_dwordx4 v[44:47], v86, s[10:11] offset:384 nt
	global_load_dwordx2 v[48:49], v87, s[12:13] nt
	global_load_dwordx2 v[50:51], v87, s[12:13] offset:64 nt
	global_load_dwordx2 v[52:53], v87, s[12:13] offset:128 nt
	global_load_dwordx2 v[54:55], v87, s[12:13] offset:192 nt
	s_add_u32 s10, s10, 0x4000
	s_addc_u32 s11, s11, 0
	s_add_u32 s12, s12, 0xe000
	s_addc_u32 s13, s13, 0
	global_load_dwordx4 v[172:175], v86, s[10:11] nt
	global_load_dwordx4 v[176:179], v86, s[10:11] offset:128 nt
	global_load_dwordx4 v[180:183], v86, s[10:11] offset:256 nt
	global_load_dwordx4 v[184:187], v86, s[10:11] offset:384 nt
	global_load_dwordx2 v[152:153], v87, s[12:13] nt
	global_load_dwordx2 v[154:155], v87, s[12:13] offset:64 nt
	global_load_dwordx2 v[156:157], v87, s[12:13] offset:128 nt
	global_load_dwordx2 v[158:159], v87, s[12:13] offset:192 nt
	s_add_u32 s10, s10, 0x4000
	s_addc_u32 s11, s11, 0
	s_add_u32 s12, s12, 0xe000
	s_addc_u32 s13, s13, 0
	global_load_dwordx4 v[192:195], v86, s[10:11] nt
	global_load_dwordx4 v[196:199], v86, s[10:11] offset:128 nt
	global_load_dwordx4 v[200:203], v86, s[10:11] offset:256 nt
	global_load_dwordx4 v[204:207], v86, s[10:11] offset:384 nt
	global_load_dwordx2 v[128:129], v87, s[12:13] nt
	global_load_dwordx2 v[130:131], v87, s[12:13] offset:64 nt
	global_load_dwordx2 v[132:133], v87, s[12:13] offset:128 nt
	global_load_dwordx2 v[134:135], v87, s[12:13] offset:192 nt
	s_add_u32 s10, s10, 0x4000
	s_addc_u32 s11, s11, 0
	s_add_u32 s12, s12, 0xe000
	s_addc_u32 s13, s13, 0
	s_waitcnt vmcnt(24)
	v_mul_f32_e32 v80, v0, v0
	v_fmac_f32_e32 v80, v1, v1
	v_lshlrev_b32_e32 v96, 16, v16
	v_fmac_f32_e32 v80, v2, v2
	v_and_b32_e32 v97, 0xffff0000, v16
	v_fmac_f32_e32 v80, v3, v3
	v_lshlrev_b32_e32 v98, 16, v17
	v_fmac_f32_e32 v80, v4, v4
	v_and_b32_e32 v99, 0xffff0000, v17
	v_fmac_f32_e32 v80, v5, v5
	v_lshlrev_b32_e32 v100, 16, v18
	v_fmac_f32_e32 v80, v6, v6
	v_and_b32_e32 v101, 0xffff0000, v18
	v_fmac_f32_e32 v80, v7, v7
	v_lshlrev_b32_e32 v102, 16, v19
	v_fmac_f32_e32 v80, v8, v8
	v_and_b32_e32 v103, 0xffff0000, v19
	v_fmac_f32_e32 v80, v9, v9
	v_lshlrev_b32_e32 v104, 16, v20
	v_fmac_f32_e32 v80, v10, v10
	v_and_b32_e32 v105, 0xffff0000, v20
	v_fmac_f32_e32 v80, v11, v11
	v_lshlrev_b32_e32 v106, 16, v21
	v_fmac_f32_e32 v80, v12, v12
	v_and_b32_e32 v107, 0xffff0000, v21
	v_fmac_f32_e32 v80, v13, v13
	v_lshlrev_b32_e32 v108, 16, v22
	v_fmac_f32_e32 v80, v14, v14
	v_and_b32_e32 v109, 0xffff0000, v22
	v_fmac_f32_e32 v80, v15, v15
	v_lshlrev_b32_e32 v110, 16, v23
	v_and_b32_e32 v111, 0xffff0000, v23
	v_mul_f32_e32 v112, 0xbfb8aa3b, v96
	v_mul_f32_e32 v113, 0xbfb8aa3b, v97
	v_mul_f32_e32 v114, 0xbfb8aa3b, v98
	v_mul_f32_e32 v115, 0xbfb8aa3b, v99
	v_mul_f32_e32 v116, 0xbfb8aa3b, v100
	v_mul_f32_e32 v117, 0xbfb8aa3b, v101
	v_mul_f32_e32 v118, 0xbfb8aa3b, v102
	v_mul_f32_e32 v119, 0xbfb8aa3b, v103
	v_mul_f32_e32 v120, 0xbfb8aa3b, v104
	v_mul_f32_e32 v121, 0xbfb8aa3b, v105
	v_mul_f32_e32 v122, 0xbfb8aa3b, v106
	v_mul_f32_e32 v123, 0xbfb8aa3b, v107
	v_mul_f32_e32 v124, 0xbfb8aa3b, v108
	v_mul_f32_e32 v125, 0xbfb8aa3b, v109
	v_mul_f32_e32 v126, 0xbfb8aa3b, v110
	v_mul_f32_e32 v127, 0xbfb8aa3b, v111
	v_add_f32_dpp v80, v80, v80 quad_perm:[1,0,3,2] row_mask:0xf bank_mask:0xf bound_ctrl:1
	v_exp_f32_e32 v112, v112
	v_exp_f32_e32 v113, v113
	v_exp_f32_e32 v114, v114
	v_exp_f32_e32 v115, v115
	v_add_f32_dpp v80, v80, v80 quad_perm:[2,3,0,1] row_mask:0xf bank_mask:0xf bound_ctrl:1
	v_exp_f32_e32 v116, v116
	v_exp_f32_e32 v117, v117
	v_exp_f32_e32 v118, v118
	v_exp_f32_e32 v119, v119
	v_add_f32_dpp v80, v80, v80 row_half_mirror row_mask:0xf bank_mask:0xf bound_ctrl:1
	v_exp_f32_e32 v120, v120
	v_exp_f32_e32 v121, v121
	v_exp_f32_e32 v122, v122
	v_exp_f32_e32 v123, v123
	v_exp_f32_e32 v124, v124
	v_exp_f32_e32 v125, v125
	v_exp_f32_e32 v126, v126
	v_exp_f32_e32 v127, v127
	v_fmamk_f32 v81, v80, 0x3c000000, v82
	v_add_f32_e32 v112, 1.0, v112
	v_add_f32_e32 v113, 1.0, v113
	v_add_f32_e32 v114, 1.0, v114
	v_add_f32_e32 v115, 1.0, v115
	v_add_f32_e32 v116, 1.0, v116
	v_add_f32_e32 v117, 1.0, v117
	v_add_f32_e32 v118, 1.0, v118
	v_add_f32_e32 v119, 1.0, v119
	v_add_f32_e32 v120, 1.0, v120
	v_add_f32_e32 v121, 1.0, v121
	v_add_f32_e32 v122, 1.0, v122
	v_add_f32_e32 v123, 1.0, v123
	v_add_f32_e32 v124, 1.0, v124
	v_add_f32_e32 v125, 1.0, v125
	v_add_f32_e32 v126, 1.0, v126
	v_add_f32_e32 v127, 1.0, v127
	v_rsq_f32_e32 v81, v81
	v_rcp_f32_e32 v112, v112
	v_rcp_f32_e32 v113, v113
	v_rcp_f32_e32 v114, v114
	v_rcp_f32_e32 v115, v115
	v_rcp_f32_e32 v116, v116
	v_rcp_f32_e32 v117, v117
	v_rcp_f32_e32 v118, v118
	v_rcp_f32_e32 v119, v119
	v_rcp_f32_e32 v120, v120
	v_rcp_f32_e32 v121, v121
	v_rcp_f32_e32 v122, v122
	v_rcp_f32_e32 v123, v123
	v_rcp_f32_e32 v124, v124
	v_rcp_f32_e32 v125, v125
	v_rcp_f32_e32 v126, v126
	v_rcp_f32_e32 v127, v127
	v_mul_f32_e32 v112, v112, v96
	v_mul_f32_e32 v113, v113, v97
	v_mul_f32_e32 v114, v114, v98
	v_mul_f32_e32 v115, v115, v99
	v_mul_f32_e32 v116, v116, v100
	v_mul_f32_e32 v117, v117, v101
	v_mul_f32_e32 v118, v118, v102
	v_mul_f32_e32 v119, v119, v103
	v_mul_f32_e32 v120, v120, v104
	v_mul_f32_e32 v121, v121, v105
	v_mul_f32_e32 v122, v122, v106
	v_mul_f32_e32 v123, v123, v107
	v_mul_f32_e32 v124, v124, v108
	v_mul_f32_e32 v125, v125, v109
	v_mul_f32_e32 v126, v126, v110
	v_mul_f32_e32 v127, v127, v111
	v_mul_f32_e32 v96, v0, v81
	v_mul_f32_e32 v97, v1, v81
	v_mul_f32_e32 v98, v2, v81
	v_mul_f32_e32 v99, v3, v81
	v_mul_f32_e32 v100, v4, v81
	v_mul_f32_e32 v101, v5, v81
	v_mul_f32_e32 v102, v6, v81
	v_mul_f32_e32 v103, v7, v81
	v_mul_f32_e32 v104, v8, v81
	v_mul_f32_e32 v105, v9, v81
	v_mul_f32_e32 v106, v10, v81
	v_mul_f32_e32 v107, v11, v81
	v_mul_f32_e32 v108, v12, v81
	v_mul_f32_e32 v109, v13, v81
	v_mul_f32_e32 v110, v14, v81
	v_mul_f32_e32 v111, v15, v81
	v_mul_f32_e32 v96, v64, v96
	v_mul_f32_e32 v97, v65, v97
	v_mul_f32_e32 v98, v66, v98
	v_mul_f32_e32 v99, v67, v99
	v_mul_f32_e32 v100, v68, v100
	v_mul_f32_e32 v101, v69, v101
	v_mul_f32_e32 v102, v70, v102
	v_mul_f32_e32 v103, v71, v103
	v_mul_f32_e32 v104, v72, v104
	v_mul_f32_e32 v105, v73, v105
	v_mul_f32_e32 v106, v74, v106
	v_mul_f32_e32 v107, v75, v107
	v_mul_f32_e32 v108, v76, v108
	v_mul_f32_e32 v109, v77, v109
	v_mul_f32_e32 v110, v78, v110
	v_mul_f32_e32 v111, v79, v111
	v_mul_f32_e32 v96, v112, v96
	v_mul_f32_e32 v97, v113, v97
	v_mul_f32_e32 v98, v114, v98
	v_mul_f32_e32 v99, v115, v99
	v_mul_f32_e32 v100, v116, v100
	v_mul_f32_e32 v101, v117, v101
	v_mul_f32_e32 v102, v118, v102
	v_mul_f32_e32 v103, v119, v103
	v_mul_f32_e32 v104, v120, v104
	v_mul_f32_e32 v105, v121, v105
	v_mul_f32_e32 v106, v122, v106
	v_mul_f32_e32 v107, v123, v107
	v_mul_f32_e32 v108, v124, v108
	v_mul_f32_e32 v109, v125, v109
	v_mul_f32_e32 v110, v126, v110
	v_mul_f32_e32 v111, v127, v111
	v_cvt_pk_bf16_f32 v144, v96, v97
	v_cvt_pk_bf16_f32 v145, v98, v99
	v_cvt_pk_bf16_f32 v146, v100, v101
	v_cvt_pk_bf16_f32 v147, v102, v103
	v_cvt_pk_bf16_f32 v148, v104, v105
	v_cvt_pk_bf16_f32 v149, v106, v107
	v_cvt_pk_bf16_f32 v150, v108, v109
	v_cvt_pk_bf16_f32 v151, v110, v111
	global_store_dwordx2 v88, v[144:145], s[14:15]
	global_store_dwordx2 v88, v[146:147], s[14:15] offset:64
	global_store_dwordx2 v88, v[148:149], s[14:15] offset:128
	global_store_dwordx2 v88, v[150:151], s[14:15] offset:192
	s_add_u32 s14, s14, 0x4000
	s_addc_u32 s15, s15, 0
	s_waitcnt vmcnt(20)
	v_mul_f32_e32 v80, v32, v32
	v_fmac_f32_e32 v80, v33, v33
	v_lshlrev_b32_e32 v96, 16, v48
	v_fmac_f32_e32 v80, v34, v34
	v_and_b32_e32 v97, 0xffff0000, v48
	v_fmac_f32_e32 v80, v35, v35
	v_lshlrev_b32_e32 v98, 16, v49
	v_fmac_f32_e32 v80, v36, v36
	v_and_b32_e32 v99, 0xffff0000, v49
	v_fmac_f32_e32 v80, v37, v37
	v_lshlrev_b32_e32 v100, 16, v50
	v_fmac_f32_e32 v80, v38, v38
	v_and_b32_e32 v101, 0xffff0000, v50
	v_fmac_f32_e32 v80, v39, v39
	v_lshlrev_b32_e32 v102, 16, v51
	v_fmac_f32_e32 v80, v40, v40
	v_and_b32_e32 v103, 0xffff0000, v51
	v_fmac_f32_e32 v80, v41, v41
	v_lshlrev_b32_e32 v104, 16, v52
	v_fmac_f32_e32 v80, v42, v42
	v_and_b32_e32 v105, 0xffff0000, v52
	v_fmac_f32_e32 v80, v43, v43
	v_lshlrev_b32_e32 v106, 16, v53
	v_fmac_f32_e32 v80, v44, v44
	v_and_b32_e32 v107, 0xffff0000, v53
	v_fmac_f32_e32 v80, v45, v45
	v_lshlrev_b32_e32 v108, 16, v54
	v_fmac_f32_e32 v80, v46, v46
	v_and_b32_e32 v109, 0xffff0000, v54
	v_fmac_f32_e32 v80, v47, v47
	v_lshlrev_b32_e32 v110, 16, v55
	v_and_b32_e32 v111, 0xffff0000, v55
	v_mul_f32_e32 v112, 0xbfb8aa3b, v96
	v_mul_f32_e32 v113, 0xbfb8aa3b, v97
	v_mul_f32_e32 v114, 0xbfb8aa3b, v98
	v_mul_f32_e32 v115, 0xbfb8aa3b, v99
	v_mul_f32_e32 v116, 0xbfb8aa3b, v100
	v_mul_f32_e32 v117, 0xbfb8aa3b, v101
	v_mul_f32_e32 v118, 0xbfb8aa3b, v102
	v_mul_f32_e32 v119, 0xbfb8aa3b, v103
	v_mul_f32_e32 v120, 0xbfb8aa3b, v104
	v_mul_f32_e32 v121, 0xbfb8aa3b, v105
	v_mul_f32_e32 v122, 0xbfb8aa3b, v106
	v_mul_f32_e32 v123, 0xbfb8aa3b, v107
	v_mul_f32_e32 v124, 0xbfb8aa3b, v108
	v_mul_f32_e32 v125, 0xbfb8aa3b, v109
	v_mul_f32_e32 v126, 0xbfb8aa3b, v110
	v_mul_f32_e32 v127, 0xbfb8aa3b, v111
	v_add_f32_dpp v80, v80, v80 quad_perm:[1,0,3,2] row_mask:0xf bank_mask:0xf bound_ctrl:1
	v_exp_f32_e32 v112, v112
	v_exp_f32_e32 v113, v113
	v_exp_f32_e32 v114, v114
	v_exp_f32_e32 v115, v115
	v_add_f32_dpp v80, v80, v80 quad_perm:[2,3,0,1] row_mask:0xf bank_mask:0xf bound_ctrl:1
	v_exp_f32_e32 v116, v116
	v_exp_f32_e32 v117, v117
	v_exp_f32_e32 v118, v118
	v_exp_f32_e32 v119, v119
	v_add_f32_dpp v80, v80, v80 row_half_mirror row_mask:0xf bank_mask:0xf bound_ctrl:1
	v_exp_f32_e32 v120, v120
	v_exp_f32_e32 v121, v121
	v_exp_f32_e32 v122, v122
	v_exp_f32_e32 v123, v123
	v_exp_f32_e32 v124, v124
	v_exp_f32_e32 v125, v125
	v_exp_f32_e32 v126, v126
	v_exp_f32_e32 v127, v127
	v_fmamk_f32 v81, v80, 0x3c000000, v82
	v_add_f32_e32 v112, 1.0, v112
	v_add_f32_e32 v113, 1.0, v113
	v_add_f32_e32 v114, 1.0, v114
	v_add_f32_e32 v115, 1.0, v115
	v_add_f32_e32 v116, 1.0, v116
	v_add_f32_e32 v117, 1.0, v117
	v_add_f32_e32 v118, 1.0, v118
	v_add_f32_e32 v119, 1.0, v119
	v_add_f32_e32 v120, 1.0, v120
	v_add_f32_e32 v121, 1.0, v121
	v_add_f32_e32 v122, 1.0, v122
	v_add_f32_e32 v123, 1.0, v123
	v_add_f32_e32 v124, 1.0, v124
	v_add_f32_e32 v125, 1.0, v125
	v_add_f32_e32 v126, 1.0, v126
	v_add_f32_e32 v127, 1.0, v127
	v_rsq_f32_e32 v81, v81
	v_rcp_f32_e32 v112, v112
	v_rcp_f32_e32 v113, v113
	v_rcp_f32_e32 v114, v114
	v_rcp_f32_e32 v115, v115
	v_rcp_f32_e32 v116, v116
	v_rcp_f32_e32 v117, v117
	v_rcp_f32_e32 v118, v118
	v_rcp_f32_e32 v119, v119
	v_rcp_f32_e32 v120, v120
	v_rcp_f32_e32 v121, v121
	v_rcp_f32_e32 v122, v122
	v_rcp_f32_e32 v123, v123
	v_rcp_f32_e32 v124, v124
	v_rcp_f32_e32 v125, v125
	v_rcp_f32_e32 v126, v126
	v_rcp_f32_e32 v127, v127
	v_mul_f32_e32 v112, v112, v96
	v_mul_f32_e32 v113, v113, v97
	v_mul_f32_e32 v114, v114, v98
	v_mul_f32_e32 v115, v115, v99
	v_mul_f32_e32 v116, v116, v100
	v_mul_f32_e32 v117, v117, v101
	v_mul_f32_e32 v118, v118, v102
	v_mul_f32_e32 v119, v119, v103
	v_mul_f32_e32 v120, v120, v104
	v_mul_f32_e32 v121, v121, v105
	v_mul_f32_e32 v122, v122, v106
	v_mul_f32_e32 v123, v123, v107
	v_mul_f32_e32 v124, v124, v108
	v_mul_f32_e32 v125, v125, v109
	v_mul_f32_e32 v126, v126, v110
	v_mul_f32_e32 v127, v127, v111
	v_mul_f32_e32 v96, v32, v81
	v_mul_f32_e32 v97, v33, v81
	v_mul_f32_e32 v98, v34, v81
	v_mul_f32_e32 v99, v35, v81
	v_mul_f32_e32 v100, v36, v81
	v_mul_f32_e32 v101, v37, v81
	v_mul_f32_e32 v102, v38, v81
	v_mul_f32_e32 v103, v39, v81
	v_mul_f32_e32 v104, v40, v81
	v_mul_f32_e32 v105, v41, v81
	v_mul_f32_e32 v106, v42, v81
	v_mul_f32_e32 v107, v43, v81
	v_mul_f32_e32 v108, v44, v81
	v_mul_f32_e32 v109, v45, v81
	v_mul_f32_e32 v110, v46, v81
	v_mul_f32_e32 v111, v47, v81
	v_mul_f32_e32 v96, v64, v96
	v_mul_f32_e32 v97, v65, v97
	v_mul_f32_e32 v98, v66, v98
	v_mul_f32_e32 v99, v67, v99
	v_mul_f32_e32 v100, v68, v100
	v_mul_f32_e32 v101, v69, v101
	v_mul_f32_e32 v102, v70, v102
	v_mul_f32_e32 v103, v71, v103
	v_mul_f32_e32 v104, v72, v104
	v_mul_f32_e32 v105, v73, v105
	v_mul_f32_e32 v106, v74, v106
	v_mul_f32_e32 v107, v75, v107
	v_mul_f32_e32 v108, v76, v108
	v_mul_f32_e32 v109, v77, v109
	v_mul_f32_e32 v110, v78, v110
	v_mul_f32_e32 v111, v79, v111
	v_mul_f32_e32 v96, v112, v96
	v_mul_f32_e32 v97, v113, v97
	v_mul_f32_e32 v98, v114, v98
	v_mul_f32_e32 v99, v115, v99
	v_mul_f32_e32 v100, v116, v100
	v_mul_f32_e32 v101, v117, v101
	v_mul_f32_e32 v102, v118, v102
	v_mul_f32_e32 v103, v119, v103
	v_mul_f32_e32 v104, v120, v104
	v_mul_f32_e32 v105, v121, v105
	v_mul_f32_e32 v106, v122, v106
	v_mul_f32_e32 v107, v123, v107
	v_mul_f32_e32 v108, v124, v108
	v_mul_f32_e32 v109, v125, v109
	v_mul_f32_e32 v110, v126, v110
	v_mul_f32_e32 v111, v127, v111
	v_cvt_pk_bf16_f32 v144, v96, v97
	v_cvt_pk_bf16_f32 v145, v98, v99
	v_cvt_pk_bf16_f32 v146, v100, v101
	v_cvt_pk_bf16_f32 v147, v102, v103
	v_cvt_pk_bf16_f32 v148, v104, v105
	v_cvt_pk_bf16_f32 v149, v106, v107
	v_cvt_pk_bf16_f32 v150, v108, v109
	v_cvt_pk_bf16_f32 v151, v110, v111
	global_store_dwordx2 v88, v[144:145], s[14:15]
	global_store_dwordx2 v88, v[146:147], s[14:15] offset:64
	global_store_dwordx2 v88, v[148:149], s[14:15] offset:128
	global_store_dwordx2 v88, v[150:151], s[14:15] offset:192
	s_add_u32 s14, s14, 0x4000
	s_addc_u32 s15, s15, 0
	s_waitcnt vmcnt(16)
	v_mul_f32_e32 v80, v172, v172
	v_fmac_f32_e32 v80, v173, v173
	v_lshlrev_b32_e32 v96, 16, v152
	v_fmac_f32_e32 v80, v174, v174
	v_and_b32_e32 v97, 0xffff0000, v152
	v_fmac_f32_e32 v80, v175, v175
	v_lshlrev_b32_e32 v98, 16, v153
	v_fmac_f32_e32 v80, v176, v176
	v_and_b32_e32 v99, 0xffff0000, v153
	v_fmac_f32_e32 v80, v177, v177
	v_lshlrev_b32_e32 v100, 16, v154
	v_fmac_f32_e32 v80, v178, v178
	v_and_b32_e32 v101, 0xffff0000, v154
	v_fmac_f32_e32 v80, v179, v179
	v_lshlrev_b32_e32 v102, 16, v155
	v_fmac_f32_e32 v80, v180, v180
	v_and_b32_e32 v103, 0xffff0000, v155
	v_fmac_f32_e32 v80, v181, v181
	v_lshlrev_b32_e32 v104, 16, v156
	v_fmac_f32_e32 v80, v182, v182
	v_and_b32_e32 v105, 0xffff0000, v156
	v_fmac_f32_e32 v80, v183, v183
	v_lshlrev_b32_e32 v106, 16, v157
	v_fmac_f32_e32 v80, v184, v184
	v_and_b32_e32 v107, 0xffff0000, v157
	v_fmac_f32_e32 v80, v185, v185
	v_lshlrev_b32_e32 v108, 16, v158
	v_fmac_f32_e32 v80, v186, v186
	v_and_b32_e32 v109, 0xffff0000, v158
	v_fmac_f32_e32 v80, v187, v187
	v_lshlrev_b32_e32 v110, 16, v159
	v_and_b32_e32 v111, 0xffff0000, v159
	v_mul_f32_e32 v112, 0xbfb8aa3b, v96
	v_mul_f32_e32 v113, 0xbfb8aa3b, v97
	v_mul_f32_e32 v114, 0xbfb8aa3b, v98
	v_mul_f32_e32 v115, 0xbfb8aa3b, v99
	v_mul_f32_e32 v116, 0xbfb8aa3b, v100
	v_mul_f32_e32 v117, 0xbfb8aa3b, v101
	v_mul_f32_e32 v118, 0xbfb8aa3b, v102
	v_mul_f32_e32 v119, 0xbfb8aa3b, v103
	v_mul_f32_e32 v120, 0xbfb8aa3b, v104
	v_mul_f32_e32 v121, 0xbfb8aa3b, v105
	v_mul_f32_e32 v122, 0xbfb8aa3b, v106
	v_mul_f32_e32 v123, 0xbfb8aa3b, v107
	v_mul_f32_e32 v124, 0xbfb8aa3b, v108
	v_mul_f32_e32 v125, 0xbfb8aa3b, v109
	v_mul_f32_e32 v126, 0xbfb8aa3b, v110
	v_mul_f32_e32 v127, 0xbfb8aa3b, v111
	v_add_f32_dpp v80, v80, v80 quad_perm:[1,0,3,2] row_mask:0xf bank_mask:0xf bound_ctrl:1
	v_exp_f32_e32 v112, v112
	v_exp_f32_e32 v113, v113
	v_exp_f32_e32 v114, v114
	v_exp_f32_e32 v115, v115
	v_add_f32_dpp v80, v80, v80 quad_perm:[2,3,0,1] row_mask:0xf bank_mask:0xf bound_ctrl:1
	v_exp_f32_e32 v116, v116
	v_exp_f32_e32 v117, v117
	v_exp_f32_e32 v118, v118
	v_exp_f32_e32 v119, v119
	v_add_f32_dpp v80, v80, v80 row_half_mirror row_mask:0xf bank_mask:0xf bound_ctrl:1
	v_exp_f32_e32 v120, v120
	v_exp_f32_e32 v121, v121
	v_exp_f32_e32 v122, v122
	v_exp_f32_e32 v123, v123
	v_exp_f32_e32 v124, v124
	v_exp_f32_e32 v125, v125
	v_exp_f32_e32 v126, v126
	v_exp_f32_e32 v127, v127
	v_fmamk_f32 v81, v80, 0x3c000000, v82
	v_add_f32_e32 v112, 1.0, v112
	v_add_f32_e32 v113, 1.0, v113
	v_add_f32_e32 v114, 1.0, v114
	v_add_f32_e32 v115, 1.0, v115
	v_add_f32_e32 v116, 1.0, v116
	v_add_f32_e32 v117, 1.0, v117
	v_add_f32_e32 v118, 1.0, v118
	v_add_f32_e32 v119, 1.0, v119
	v_add_f32_e32 v120, 1.0, v120
	v_add_f32_e32 v121, 1.0, v121
	v_add_f32_e32 v122, 1.0, v122
	v_add_f32_e32 v123, 1.0, v123
	v_add_f32_e32 v124, 1.0, v124
	v_add_f32_e32 v125, 1.0, v125
	v_add_f32_e32 v126, 1.0, v126
	v_add_f32_e32 v127, 1.0, v127
	v_rsq_f32_e32 v81, v81
	v_rcp_f32_e32 v112, v112
	v_rcp_f32_e32 v113, v113
	v_rcp_f32_e32 v114, v114
	v_rcp_f32_e32 v115, v115
	v_rcp_f32_e32 v116, v116
	v_rcp_f32_e32 v117, v117
	v_rcp_f32_e32 v118, v118
	v_rcp_f32_e32 v119, v119
	v_rcp_f32_e32 v120, v120
	v_rcp_f32_e32 v121, v121
	v_rcp_f32_e32 v122, v122
	v_rcp_f32_e32 v123, v123
	v_rcp_f32_e32 v124, v124
	v_rcp_f32_e32 v125, v125
	v_rcp_f32_e32 v126, v126
	v_rcp_f32_e32 v127, v127
	v_mul_f32_e32 v112, v112, v96
	v_mul_f32_e32 v113, v113, v97
	v_mul_f32_e32 v114, v114, v98
	v_mul_f32_e32 v115, v115, v99
	v_mul_f32_e32 v116, v116, v100
	v_mul_f32_e32 v117, v117, v101
	v_mul_f32_e32 v118, v118, v102
	v_mul_f32_e32 v119, v119, v103
	v_mul_f32_e32 v120, v120, v104
	v_mul_f32_e32 v121, v121, v105
	v_mul_f32_e32 v122, v122, v106
	v_mul_f32_e32 v123, v123, v107
	v_mul_f32_e32 v124, v124, v108
	v_mul_f32_e32 v125, v125, v109
	v_mul_f32_e32 v126, v126, v110
	v_mul_f32_e32 v127, v127, v111
	v_mul_f32_e32 v96, v172, v81
	v_mul_f32_e32 v97, v173, v81
	v_mul_f32_e32 v98, v174, v81
	v_mul_f32_e32 v99, v175, v81
	v_mul_f32_e32 v100, v176, v81
	v_mul_f32_e32 v101, v177, v81
	v_mul_f32_e32 v102, v178, v81
	v_mul_f32_e32 v103, v179, v81
	v_mul_f32_e32 v104, v180, v81
	v_mul_f32_e32 v105, v181, v81
	v_mul_f32_e32 v106, v182, v81
	v_mul_f32_e32 v107, v183, v81
	v_mul_f32_e32 v108, v184, v81
	v_mul_f32_e32 v109, v185, v81
	v_mul_f32_e32 v110, v186, v81
	v_mul_f32_e32 v111, v187, v81
	v_mul_f32_e32 v96, v64, v96
	v_mul_f32_e32 v97, v65, v97
	v_mul_f32_e32 v98, v66, v98
	v_mul_f32_e32 v99, v67, v99
	v_mul_f32_e32 v100, v68, v100
	v_mul_f32_e32 v101, v69, v101
	v_mul_f32_e32 v102, v70, v102
	v_mul_f32_e32 v103, v71, v103
	v_mul_f32_e32 v104, v72, v104
	v_mul_f32_e32 v105, v73, v105
	v_mul_f32_e32 v106, v74, v106
	v_mul_f32_e32 v107, v75, v107
	v_mul_f32_e32 v108, v76, v108
	v_mul_f32_e32 v109, v77, v109
	v_mul_f32_e32 v110, v78, v110
	v_mul_f32_e32 v111, v79, v111
	v_mul_f32_e32 v96, v112, v96
	v_mul_f32_e32 v97, v113, v97
	v_mul_f32_e32 v98, v114, v98
	v_mul_f32_e32 v99, v115, v99
	v_mul_f32_e32 v100, v116, v100
	v_mul_f32_e32 v101, v117, v101
	v_mul_f32_e32 v102, v118, v102
	v_mul_f32_e32 v103, v119, v103
	v_mul_f32_e32 v104, v120, v104
	v_mul_f32_e32 v105, v121, v105
	v_mul_f32_e32 v106, v122, v106
	v_mul_f32_e32 v107, v123, v107
	v_mul_f32_e32 v108, v124, v108
	v_mul_f32_e32 v109, v125, v109
	v_mul_f32_e32 v110, v126, v110
	v_mul_f32_e32 v111, v127, v111
	v_cvt_pk_bf16_f32 v144, v96, v97
	v_cvt_pk_bf16_f32 v145, v98, v99
	v_cvt_pk_bf16_f32 v146, v100, v101
	v_cvt_pk_bf16_f32 v147, v102, v103
	v_cvt_pk_bf16_f32 v148, v104, v105
	v_cvt_pk_bf16_f32 v149, v106, v107
	v_cvt_pk_bf16_f32 v150, v108, v109
	v_cvt_pk_bf16_f32 v151, v110, v111
	global_store_dwordx2 v88, v[144:145], s[14:15]
	global_store_dwordx2 v88, v[146:147], s[14:15] offset:64
	global_store_dwordx2 v88, v[148:149], s[14:15] offset:128
	global_store_dwordx2 v88, v[150:151], s[14:15] offset:192
	s_add_u32 s14, s14, 0x4000
	s_addc_u32 s15, s15, 0
	s_waitcnt vmcnt(12)
	v_mul_f32_e32 v80, v192, v192
	v_fmac_f32_e32 v80, v193, v193
	v_lshlrev_b32_e32 v96, 16, v128
	v_fmac_f32_e32 v80, v194, v194
	v_and_b32_e32 v97, 0xffff0000, v128
	v_fmac_f32_e32 v80, v195, v195
	v_lshlrev_b32_e32 v98, 16, v129
	v_fmac_f32_e32 v80, v196, v196
	v_and_b32_e32 v99, 0xffff0000, v129
	v_fmac_f32_e32 v80, v197, v197
	v_lshlrev_b32_e32 v100, 16, v130
	v_fmac_f32_e32 v80, v198, v198
	v_and_b32_e32 v101, 0xffff0000, v130
	v_fmac_f32_e32 v80, v199, v199
	v_lshlrev_b32_e32 v102, 16, v131
	v_fmac_f32_e32 v80, v200, v200
	v_and_b32_e32 v103, 0xffff0000, v131
	v_fmac_f32_e32 v80, v201, v201
	v_lshlrev_b32_e32 v104, 16, v132
	v_fmac_f32_e32 v80, v202, v202
	v_and_b32_e32 v105, 0xffff0000, v132
	v_fmac_f32_e32 v80, v203, v203
	v_lshlrev_b32_e32 v106, 16, v133
	v_fmac_f32_e32 v80, v204, v204
	v_and_b32_e32 v107, 0xffff0000, v133
	v_fmac_f32_e32 v80, v205, v205
	v_lshlrev_b32_e32 v108, 16, v134
	v_fmac_f32_e32 v80, v206, v206
	v_and_b32_e32 v109, 0xffff0000, v134
	v_fmac_f32_e32 v80, v207, v207
	v_lshlrev_b32_e32 v110, 16, v135
	v_and_b32_e32 v111, 0xffff0000, v135
	v_mul_f32_e32 v112, 0xbfb8aa3b, v96
	v_mul_f32_e32 v113, 0xbfb8aa3b, v97
	v_mul_f32_e32 v114, 0xbfb8aa3b, v98
	v_mul_f32_e32 v115, 0xbfb8aa3b, v99
	v_mul_f32_e32 v116, 0xbfb8aa3b, v100
	v_mul_f32_e32 v117, 0xbfb8aa3b, v101
	v_mul_f32_e32 v118, 0xbfb8aa3b, v102
	v_mul_f32_e32 v119, 0xbfb8aa3b, v103
	v_mul_f32_e32 v120, 0xbfb8aa3b, v104
	v_mul_f32_e32 v121, 0xbfb8aa3b, v105
	v_mul_f32_e32 v122, 0xbfb8aa3b, v106
	v_mul_f32_e32 v123, 0xbfb8aa3b, v107
	v_mul_f32_e32 v124, 0xbfb8aa3b, v108
	v_mul_f32_e32 v125, 0xbfb8aa3b, v109
	v_mul_f32_e32 v126, 0xbfb8aa3b, v110
	v_mul_f32_e32 v127, 0xbfb8aa3b, v111
	v_add_f32_dpp v80, v80, v80 quad_perm:[1,0,3,2] row_mask:0xf bank_mask:0xf bound_ctrl:1
	v_exp_f32_e32 v112, v112
	v_exp_f32_e32 v113, v113
	v_exp_f32_e32 v114, v114
	v_exp_f32_e32 v115, v115
	v_add_f32_dpp v80, v80, v80 quad_perm:[2,3,0,1] row_mask:0xf bank_mask:0xf bound_ctrl:1
	v_exp_f32_e32 v116, v116
	v_exp_f32_e32 v117, v117
	v_exp_f32_e32 v118, v118
	v_exp_f32_e32 v119, v119
	v_add_f32_dpp v80, v80, v80 row_half_mirror row_mask:0xf bank_mask:0xf bound_ctrl:1
	v_exp_f32_e32 v120, v120
	v_exp_f32_e32 v121, v121
	v_exp_f32_e32 v122, v122
	v_exp_f32_e32 v123, v123
	v_exp_f32_e32 v124, v124
	v_exp_f32_e32 v125, v125
	v_exp_f32_e32 v126, v126
	v_exp_f32_e32 v127, v127
	v_fmamk_f32 v81, v80, 0x3c000000, v82
	v_add_f32_e32 v112, 1.0, v112
	v_add_f32_e32 v113, 1.0, v113
	v_add_f32_e32 v114, 1.0, v114
	v_add_f32_e32 v115, 1.0, v115
	v_add_f32_e32 v116, 1.0, v116
	v_add_f32_e32 v117, 1.0, v117
	v_add_f32_e32 v118, 1.0, v118
	v_add_f32_e32 v119, 1.0, v119
	v_add_f32_e32 v120, 1.0, v120
	v_add_f32_e32 v121, 1.0, v121
	v_add_f32_e32 v122, 1.0, v122
	v_add_f32_e32 v123, 1.0, v123
	v_add_f32_e32 v124, 1.0, v124
	v_add_f32_e32 v125, 1.0, v125
	v_add_f32_e32 v126, 1.0, v126
	v_add_f32_e32 v127, 1.0, v127
	v_rsq_f32_e32 v81, v81
	v_rcp_f32_e32 v112, v112
	v_rcp_f32_e32 v113, v113
	v_rcp_f32_e32 v114, v114
	v_rcp_f32_e32 v115, v115
	v_rcp_f32_e32 v116, v116
	v_rcp_f32_e32 v117, v117
	v_rcp_f32_e32 v118, v118
	v_rcp_f32_e32 v119, v119
	v_rcp_f32_e32 v120, v120
	v_rcp_f32_e32 v121, v121
	v_rcp_f32_e32 v122, v122
	v_rcp_f32_e32 v123, v123
	v_rcp_f32_e32 v124, v124
	v_rcp_f32_e32 v125, v125
	v_rcp_f32_e32 v126, v126
	v_rcp_f32_e32 v127, v127
	v_mul_f32_e32 v112, v112, v96
	v_mul_f32_e32 v113, v113, v97
	v_mul_f32_e32 v114, v114, v98
	v_mul_f32_e32 v115, v115, v99
	v_mul_f32_e32 v116, v116, v100
	v_mul_f32_e32 v117, v117, v101
	v_mul_f32_e32 v118, v118, v102
	v_mul_f32_e32 v119, v119, v103
	v_mul_f32_e32 v120, v120, v104
	v_mul_f32_e32 v121, v121, v105
	v_mul_f32_e32 v122, v122, v106
	v_mul_f32_e32 v123, v123, v107
	v_mul_f32_e32 v124, v124, v108
	v_mul_f32_e32 v125, v125, v109
	v_mul_f32_e32 v126, v126, v110
	v_mul_f32_e32 v127, v127, v111
	v_mul_f32_e32 v96, v192, v81
	v_mul_f32_e32 v97, v193, v81
	v_mul_f32_e32 v98, v194, v81
	v_mul_f32_e32 v99, v195, v81
	v_mul_f32_e32 v100, v196, v81
	v_mul_f32_e32 v101, v197, v81
	v_mul_f32_e32 v102, v198, v81
	v_mul_f32_e32 v103, v199, v81
	v_mul_f32_e32 v104, v200, v81
	v_mul_f32_e32 v105, v201, v81
	v_mul_f32_e32 v106, v202, v81
	v_mul_f32_e32 v107, v203, v81
	v_mul_f32_e32 v108, v204, v81
	v_mul_f32_e32 v109, v205, v81
	v_mul_f32_e32 v110, v206, v81
	v_mul_f32_e32 v111, v207, v81
	v_mul_f32_e32 v96, v64, v96
	v_mul_f32_e32 v97, v65, v97
	v_mul_f32_e32 v98, v66, v98
	v_mul_f32_e32 v99, v67, v99
	v_mul_f32_e32 v100, v68, v100
	v_mul_f32_e32 v101, v69, v101
	v_mul_f32_e32 v102, v70, v102
	v_mul_f32_e32 v103, v71, v103
	v_mul_f32_e32 v104, v72, v104
	v_mul_f32_e32 v105, v73, v105
	v_mul_f32_e32 v106, v74, v106
	v_mul_f32_e32 v107, v75, v107
	v_mul_f32_e32 v108, v76, v108
	v_mul_f32_e32 v109, v77, v109
	v_mul_f32_e32 v110, v78, v110
	v_mul_f32_e32 v111, v79, v111
	v_mul_f32_e32 v96, v112, v96
	v_mul_f32_e32 v97, v113, v97
	v_mul_f32_e32 v98, v114, v98
	v_mul_f32_e32 v99, v115, v99
	v_mul_f32_e32 v100, v116, v100
	v_mul_f32_e32 v101, v117, v101
	v_mul_f32_e32 v102, v118, v102
	v_mul_f32_e32 v103, v119, v103
	v_mul_f32_e32 v104, v120, v104
	v_mul_f32_e32 v105, v121, v105
	v_mul_f32_e32 v106, v122, v106
	v_mul_f32_e32 v107, v123, v107
	v_mul_f32_e32 v108, v124, v108
	v_mul_f32_e32 v109, v125, v109
	v_mul_f32_e32 v110, v126, v110
	v_mul_f32_e32 v111, v127, v111
	v_cvt_pk_bf16_f32 v144, v96, v97
	v_cvt_pk_bf16_f32 v145, v98, v99
	v_cvt_pk_bf16_f32 v146, v100, v101
	v_cvt_pk_bf16_f32 v147, v102, v103
	v_cvt_pk_bf16_f32 v148, v104, v105
	v_cvt_pk_bf16_f32 v149, v106, v107
	v_cvt_pk_bf16_f32 v150, v108, v109
	v_cvt_pk_bf16_f32 v151, v110, v111
	global_store_dwordx2 v88, v[144:145], s[14:15]
	global_store_dwordx2 v88, v[146:147], s[14:15] offset:64
	global_store_dwordx2 v88, v[148:149], s[14:15] offset:128
	global_store_dwordx2 v88, v[150:151], s[14:15] offset:192
	s_add_u32 s14, s14, 0x4000
	s_addc_u32 s15, s15, 0

.LBB0_1002:
	v_ashrrev_i32_e32 v10, 8, v219
	v_mul_hi_i32 v0, v10, s3
	v_lshrrev_b32_e32 v2, 31, v0
	v_ashrrev_i32_e32 v0, 2, v0
	v_add_u32_e32 v14, v0, v2
	v_and_b32_e32 v0, 7, v14
	v_cmp_ne_u32_e32 vcc, 0, v0
	s_and_saveexec_b64 s[18:19], vcc
	s_cbranch_execz .LBB0_1001
	v_mul_lo_u32 v0, v14, 22
	v_ashrrev_i32_e32 v11, 31, v10
	v_bfe_u32 v15, v219, 7, 1
	v_and_b32_e32 v3, 0x7f, v219
	v_sub_u32_e32 v0, v10, v0
	v_lshlrev_b64 v[4:5], 11, v[10:11]
	v_lshl_or_b32 v2, v0, 7, v3
	v_lshl_add_u64 v[4:5], s[12:13], 0, v[4:5]
	v_lshlrev_b32_e32 v0, 10, v15
	v_lshl_add_u64 v[4:5], v[4:5], 0, v[0:1]
	v_lshlrev_b32_e32 v0, 2, v3
	v_ashrrev_i32_e32 v3, 31, v2
	v_lshl_add_u64 v[8:9], v[2:3], 2, s[40:41]
	v_lshl_add_u64 v[6:7], v[4:5], 0, v[0:1]
	v_add_co_u32_e32 v12, vcc, 0x2000, v8
	global_load_dword v5, v[6:7], off nt
	global_load_dword v4, v[6:7], off offset:512 nt
	v_addc_co_u32_e32 v13, vcc, 0, v9, vcc
	global_load_dword v7, v[8:9], off nt
	global_load_dword v6, v[12:13], off offset:3072 nt
	v_subrev_u32_e32 v10, 22, v10
	v_ashrrev_i32_e32 v11, 31, v10
	v_lshlrev_b64 v[10:11], 11, v[10:11]
	v_and_b32_e32 v12, 0x80, v219
	v_lshl_add_u64 v[10:11], s[10:11], 0, v[10:11]
	v_cmp_ne_u32_e32 vcc, 0, v12
	s_and_saveexec_b64 s[20:21], vcc
	s_xor_b64 s[20:21], exec, s[20:21]
	s_cbranch_execz .LBB0_1005
	v_lshl_add_u64 v[8:9], v[10:11], 0, v[0:1]
	global_load_dword v11, v[8:9], off offset:1024 nt
	global_load_dword v10, v[8:9], off offset:1536 nt
	s_waitcnt vmcnt(0)
	v_pk_mul_f32 v[12:13], v[6:7], v[10:11]
.LBB0_1005:
	s_andn2_saveexec_b64 s[20:21], s[20:21]
	s_cbranch_execz .LBB0_1000
	v_add_co_u32_e32 v12, vcc, 0x8000, v8
	s_nop 1
	v_addc_co_u32_e32 v13, vcc, 0, v9, vcc
	v_add_co_u32_e32 v8, vcc, 0x5000, v8
	s_nop 1
	v_addc_co_u32_e32 v9, vcc, 0, v9, vcc
	global_load_dword v16, v[12:13], off offset:1024 nt
	global_load_dword v17, v[8:9], off offset:2048 nt
	v_lshl_add_u64 v[8:9], v[10:11], 0, v[0:1]
	global_load_dword v11, v[8:9], off nt
	global_load_dword v13, v[8:9], off offset:1024 nt
	global_load_dword v12, v[8:9], off offset:1536 nt
	global_load_dword v10, v[8:9], off offset:512 nt
	s_waitcnt vmcnt(1)
	v_pk_mul_f32 v[8:9], v[16:17], v[12:13]
	s_waitcnt vmcnt(0)
	v_pk_fma_f32 v[12:13], v[6:7], v[10:11], v[8:9]
	s_branch .LBB0_1000
